# prompt diff-attention rewritten as a 32-key sub-tile software pipeline (PV(n-1) and QK(n+1) MFMAs overlap softmax(n) VALU), one barrier per 64-key tile, counted vmcnt; rescale check per 32 keys (same
# baseline (speedup 1.0000x reference)
; #define LAS __attribute__((address_space(3)))
; #define DIFF_ISSUE(T_) do { const unsigned sb_ = lbase + (unsigned)((T_) & 3) * 32768u; const bf16* k_ = gk + (size_t)(T_) * (64 * 512); const bf16* v_ = gv + (size_t)(T_) * 64; \
;         glds16(k_, sb_); glds16(k_ + 64, sb_ + 8192u); glds16(v_, sb_ + 16384u); glds16(v_ + (size_t)64 * VPITCH, sb_ + 24576u); } while (0)
; __device__ __forceinline__ void diff_unit_lds(LAS unsigned char* lds, const bf16* Qd, const bf16* Kd, const bf16* VdT, bf16* MIX, const float* ghead, float lam, int head, int u, int wave, int lane) {
;     const int h = lane >> 5, r = lane & 31, kap = kappa(r), slot = wave & 3, comp = wave >> 2;
;     const int row = 128 * u + 32 * slot + r;
;     const int nT = 2 * u + 3, Tlast = 2 * u + 1 + (slot >> 1);
;     const bf16* qrow = Qd + (size_t)row * 512 + head * 128 + comp * 64;
;     bf16x8 qf[4];
; #pragma unroll
;     for (int ds = 0; ds < 4; ++ds) qf[ds] = *(const bf16x8*)(qrow + 16 * ds + 8 * h);
;     const int koff = comp * 8192 + kap * 128, kx = (kap >> 1) & 7;
;     const int voff = 16384 + r * 128, vx = (r >> 1) & 7;
;     const int srow = 8 * wave + (lane >> 3), sc = (lane & 7) ^ ((srow >> 1) & 7);
;     const bf16* gk = Kd + (size_t)srow * 512 + head * 128 + sc * 8;
;     const bf16* gv = VdT + (size_t)(head * 128 + srow) * VPITCH + sc * 8;
;     const unsigned lbase = (unsigned)(size_t)lds + (unsigned)wave * 1024u;
;     ...
;     f32x16 O[4]; float m_used = 0.f, l = 0.f;
;     f32x16 NEGM;
; #pragma unroll
;     for (int i = 0; i < 16; ++i) NEGM[i] = 0.f;
; #pragma unroll
;     for (int b = 0; b < 4; ++b)
; #pragma unroll
;         for (int i = 0; i < 16; ++i) O[b][i] = 0.f;
;     asm volatile("" : "+v"(qf[0]), "+v"(qf[1]), "+v"(qf[2]), "+v"(qf[3]));
;     asm volatile("s_waitcnt vmcnt(0)" ::: "memory");
;     DIFF_ISSUE(0); DIFF_ISSUE(1);
; #pragma unroll 2
;     for (int T = 0; T < nT; ++T) {
;         LAS unsigned char* st = lds + (T & 3) * 32768;
;         if ((T & 1) == 0) {
;             asm volatile("s_waitcnt vmcnt(0) lgkmcnt(0)\n\ts_barrier" ::: "memory");
;             if (T + 2 < nT) DIFF_ISSUE(T + 2);
;             if (T + 3 < nT) DIFF_ISSUE(T + 3);
.LBB0_452:
	s_and_b64 s[0:1], s[34:35], exec
	s_cselect_b32 s0, s89, s90
	v_lshl_or_b32 v190, s0, 7, v139
	v_ashrrev_i32_e32 v191, 31, v190
	v_lshlrev_b64 v[2:3], 10, v[190:191]
	v_lshl_add_u64 v[2:3], v[154:155], 0, v[2:3]
	global_load_dwordx4 v[114:117], v[2:3], off offset:96
	global_load_dwordx4 v[118:121], v[2:3], off offset:64
	global_load_dwordx4 v[122:125], v[2:3], off offset:32
	global_load_dwordx4 v[126:129], v[2:3], off
	v_mov_b32_e32 v65, 0
	v_mov_b32_e32 v64, 0
	v_mov_b32_e32 v63, 0
	v_mov_b32_e32 v62, 0
	v_mov_b32_e32 v61, 0
	v_mov_b32_e32 v60, 0
	v_mov_b32_e32 v59, 0
	v_mov_b32_e32 v58, 0
	v_mov_b32_e32 v57, 0
	v_mov_b32_e32 v56, 0
	v_mov_b32_e32 v55, 0
	v_mov_b32_e32 v54, 0
	v_mov_b32_e32 v53, 0
	v_mov_b32_e32 v52, 0
	v_mov_b32_e32 v51, 0
	v_mov_b32_e32 v50, 0
	v_mov_b32_e32 v49, 0
	v_mov_b32_e32 v48, 0
	v_mov_b32_e32 v47, 0
	v_mov_b32_e32 v46, 0
	v_mov_b32_e32 v45, 0
	v_mov_b32_e32 v44, 0
	v_mov_b32_e32 v43, 0
	v_mov_b32_e32 v42, 0
	v_mov_b32_e32 v41, 0
	v_mov_b32_e32 v40, 0
	v_mov_b32_e32 v39, 0
	v_mov_b32_e32 v38, 0
	v_mov_b32_e32 v37, 0
	v_mov_b32_e32 v36, 0
	v_mov_b32_e32 v35, 0
	v_mov_b32_e32 v34, 0
	v_mov_b32_e32 v33, 0
	v_mov_b32_e32 v32, 0
	v_mov_b32_e32 v31, 0
	v_mov_b32_e32 v30, 0
	v_mov_b32_e32 v29, 0
	v_mov_b32_e32 v28, 0
	v_mov_b32_e32 v27, 0
	v_mov_b32_e32 v26, 0
	v_mov_b32_e32 v25, 0
	v_mov_b32_e32 v24, 0
	v_mov_b32_e32 v23, 0
	v_mov_b32_e32 v22, 0
	v_mov_b32_e32 v21, 0
	v_mov_b32_e32 v20, 0
	v_mov_b32_e32 v19, 0
	v_mov_b32_e32 v18, 0
	v_mov_b32_e32 v17, 0
	v_mov_b32_e32 v16, 0
	v_mov_b32_e32 v15, 0
	v_mov_b32_e32 v14, 0
	v_mov_b32_e32 v13, 0
	v_mov_b32_e32 v12, 0
	v_mov_b32_e32 v11, 0
	v_mov_b32_e32 v10, 0
	v_mov_b32_e32 v9, 0
	v_mov_b32_e32 v8, 0
	v_mov_b32_e32 v7, 0
	v_mov_b32_e32 v6, 0
	v_mov_b32_e32 v5, 0
	s_cmp_lt_i32 s0, -1
	v_mov_b32_e32 v4, 0
	v_mov_b32_e32 v3, 0
	v_mov_b32_e32 v2, 0
	v_mov_b32_e32 v218, 0
	s_waitcnt vmcnt(0)
	s_waitcnt vmcnt(0)
	s_mov_b32 s57, s0
	s_mov_b32 s7, m0
	s_mov_b32 s8, 0x0
	s_mov_b32 s9, 0
	v_lshl_add_u64 v[180:181], v[158:159], 0, s[8:9]
	s_add_i32 s0, s33, 0x0
	s_mov_b32 m0, s0
	s_nop 0
	global_load_lds_dwordx4 v[180:181], off
	s_mov_b32 s8, 0x80
	s_mov_b32 s9, 0
	v_lshl_add_u64 v[182:183], v[158:159], 0, s[8:9]
	s_add_i32 s0, s33, 0x2000
	s_mov_b32 m0, s0
	s_nop 0
	global_load_lds_dwordx4 v[182:183], off
	s_mov_b32 s8, 0x0
	s_mov_b32 s9, 0
	v_lshl_add_u64 v[184:185], v[156:157], 0, s[8:9]
	s_add_i32 s0, s33, 0x4000
	s_mov_b32 m0, s0
	s_nop 0
	global_load_lds_dwordx4 v[184:185], off
	s_mov_b32 s8, 0x0
	s_mov_b32 s9, 0
	v_lshl_add_u64 v[186:187], v[162:163], 0, s[8:9]
	s_add_i32 s0, s33, 0x6000
	s_mov_b32 m0, s0
	s_nop 0
	global_load_lds_dwordx4 v[186:187], off
	s_mov_b32 s8, 0x10000
	s_mov_b32 s9, 0
	v_lshl_add_u64 v[180:181], v[158:159], 0, s[8:9]
	s_add_i32 s0, s33, 0x8000
	s_mov_b32 m0, s0
	s_nop 0
	global_load_lds_dwordx4 v[180:181], off
	s_mov_b32 s8, 0x10080
	s_mov_b32 s9, 0
	v_lshl_add_u64 v[182:183], v[158:159], 0, s[8:9]
	s_add_i32 s0, s33, 0xa000
	s_mov_b32 m0, s0
	s_nop 0
	global_load_lds_dwordx4 v[182:183], off
	s_mov_b32 s8, 0x80
	s_mov_b32 s9, 0
	v_lshl_add_u64 v[184:185], v[156:157], 0, s[8:9]
	s_add_i32 s0, s33, 0xc000
	s_mov_b32 m0, s0
	s_nop 0
	global_load_lds_dwordx4 v[184:185], off
	s_mov_b32 s8, 0x80
	s_mov_b32 s9, 0
	v_lshl_add_u64 v[186:187], v[162:163], 0, s[8:9]
	s_add_i32 s0, s33, 0xe000
	s_mov_b32 m0, s0
	s_nop 0
	global_load_lds_dwordx4 v[186:187], off
	s_waitcnt vmcnt(0) lgkmcnt(0)
	s_barrier
	s_mov_b32 s8, 0x20000
	s_mov_b32 s9, 0
	v_lshl_add_u64 v[180:181], v[158:159], 0, s[8:9]
	s_add_i32 s0, s33, 0x10000
	s_mov_b32 m0, s0
	s_nop 0
	global_load_lds_dwordx4 v[180:181], off
	s_mov_b32 s8, 0x20080
	s_mov_b32 s9, 0
	v_lshl_add_u64 v[182:183], v[158:159], 0, s[8:9]
	s_add_i32 s0, s33, 0x12000
	s_mov_b32 m0, s0
	s_nop 0
	global_load_lds_dwordx4 v[182:183], off
	s_mov_b32 s8, 0x100
	s_mov_b32 s9, 0
	v_lshl_add_u64 v[184:185], v[156:157], 0, s[8:9]
	s_add_i32 s0, s33, 0x14000
	s_mov_b32 m0, s0
	s_nop 0
	global_load_lds_dwordx4 v[184:185], off
	s_mov_b32 s8, 0x100
	s_mov_b32 s9, 0
	v_lshl_add_u64 v[186:187], v[162:163], 0, s[8:9]
	s_add_i32 s0, s33, 0x16000
	s_mov_b32 m0, s0
	s_nop 0
	global_load_lds_dwordx4 v[186:187], off
	s_cmp_lt_i32 s57, 1
	s_cbranch_scc1 .Lq_no_t3
	s_mov_b32 s8, 0x30000
	s_mov_b32 s9, 0
	v_lshl_add_u64 v[180:181], v[158:159], 0, s[8:9]
	s_add_i32 s0, s33, 0x18000
	s_mov_b32 m0, s0
	s_nop 0
	global_load_lds_dwordx4 v[180:181], off
	s_mov_b32 s8, 0x30080
	s_mov_b32 s9, 0
	v_lshl_add_u64 v[182:183], v[158:159], 0, s[8:9]
	s_add_i32 s0, s33, 0x1a000
	s_mov_b32 m0, s0
	s_nop 0
	global_load_lds_dwordx4 v[182:183], off
	s_mov_b32 s8, 0x180
	s_mov_b32 s9, 0
	v_lshl_add_u64 v[184:185], v[156:157], 0, s[8:9]
	s_add_i32 s0, s33, 0x1c000
	s_mov_b32 m0, s0
	s_nop 0
	global_load_lds_dwordx4 v[184:185], off
	s_mov_b32 s8, 0x180
	s_mov_b32 s9, 0
	v_lshl_add_u64 v[186:187], v[162:163], 0, s[8:9]
	s_add_i32 s0, s33, 0x1e000
	s_mov_b32 m0, s0
	s_nop 0
	global_load_lds_dwordx4 v[186:187], off
; __device__ __forceinline__ void diff_unit_lds(LAS unsigned char* lds, const bf16* Qd, const bf16* Kd, const bf16* VdT, bf16* MIX, const float* ghead, float lam, int head, int u, int wave, int lane) {
;     ...
;     for (int T = 0; T < nT; ++T) {
;         LAS unsigned char* st = lds + (T & 3) * 32768;
;         if ((T & 1) == 0) {
;             asm volatile("s_waitcnt vmcnt(0) lgkmcnt(0)\n\ts_barrier" ::: "memory");
;             if (T + 2 < nT) DIFF_ISSUE(T + 2);
;             if (T + 3 < nT) DIFF_ISSUE(T + 3);
;         }
;         if (T <= Tlast) {
;             const bool part = (T == Tlast);
;             const bool masked = part && (h == 1);
;             f32x16 S0 = NEGM, S1 = NEGM;
; #pragma unroll
;             for (int ds = 0; ds < 4; ++ds) S0 = MFMA32(*(const LAS bf16x8*)(st + koff + (((2 * ds + h) ^ kx) << 4)), qf[ds], S0);
;             if (!part) {
; #pragma unroll
;                 for (int ds = 0; ds < 4; ++ds) S1 = MFMA32(*(const LAS bf16x8*)(st + koff + 4096 + (((2 * ds + h) ^ kx) << 4)), qf[ds], S1);
;             }
;             float tmax = S0[0];
; #pragma unroll
;             for (int i = 1; i < 16; ++i) tmax = fmaxf(tmax, S0[i]);
;             if (masked) tmax = -1e30f;
;             if (!part) {
; #pragma unroll
;                 for (int i = 0; i < 16; ++i) tmax = fmaxf(tmax, S1[i]);
;             }
;             tmax = fmaxf(tmax, xhalf(tmax, h));
;             if (T == 0 || __any(tmax > 8.0f)) {
;                 const float delta = (T == 0) ? tmax : fmaxf(tmax, 0.f), alpha = (T == 0) ? 1.0f : __builtin_amdgcn_exp2f(-delta);
;                 l *= alpha;
; #pragma unroll
;                 for (int b = 0; b < 4; ++b)
; #pragma unroll
;                     for (int i = 0; i < 16; ++i) O[b][i] *= alpha;
;                 m_used += delta;
; #pragma unroll
;                 for (int i = 0; i < 16; ++i) { NEGM[i] = -m_used; S0[i] -= delta; S1[i] -= delta; }
;             }
;             {
;                 float p[16]; float ps = 0.f;
; #pragma unroll
;                 for (int i = 0; i < 16; ++i) { p[i] = __builtin_amdgcn_exp2f(S0[i]); ps += p[i]; }
;                 if (masked) {
; #pragma unroll
;                     for (int i = 0; i < 16; ++i) p[i] = 0.f;
;                     ps = 0.f;
;                 }
;                 l += ps;
;                 const bf16x8 pk0 = pack8(p[0], p[1], p[2], p[3], p[4], p[5], p[6], p[7]);
.Lq_no_t3:
	s_mov_b32 m0, s7
	s_lshl_b32 s93, s57, 1
	s_or_b32 s91, s23, s93
	s_add_i32 s91, s91, 1
	s_lshl_b32 s92, s91, 1
	s_mov_b32 s94, 0
	s_mov_b32 s96, 0xff800000
	s_mov_b32 s97, 0xff800000
	s_mov_b32 s59, 0
	v_mov_b32_e32 v66, 0
	v_mov_b32_e32 v67, 0
	v_mov_b32_e32 v68, 0
	v_mov_b32_e32 v69, 0
	v_mov_b32_e32 v70, 0
	v_mov_b32_e32 v71, 0
	v_mov_b32_e32 v72, 0
	v_mov_b32_e32 v73, 0
	v_mov_b32_e32 v74, 0
	v_mov_b32_e32 v75, 0
	v_mov_b32_e32 v76, 0
	v_mov_b32_e32 v77, 0
	v_mov_b32_e32 v78, 0
	v_mov_b32_e32 v79, 0
	v_mov_b32_e32 v80, 0
	v_mov_b32_e32 v81, 0
	v_mov_b32_e32 v219, 0
	v_mov_b32_e32 v82, 0
	v_mov_b32_e32 v83, 0
	v_mov_b32_e32 v84, 0
	v_mov_b32_e32 v85, 0
	v_mov_b32_e32 v86, 0
	v_mov_b32_e32 v87, 0
	v_mov_b32_e32 v88, 0
	v_mov_b32_e32 v89, 0
	v_mov_b32_e32 v220, 0
	v_mov_b32_e32 v221, 0
	v_mov_b32_e32 v222, 0
	v_mov_b32_e32 v223, 0
	v_mov_b32_e32 v226, 0
	v_mov_b32_e32 v227, 0
	v_mov_b32_e32 v228, 0
	v_mov_b32_e32 v229, 0
	v_mov_b32_e32 v230, 0
	v_mov_b32_e32 v231, 0
	v_mov_b32_e32 v232, 0
	v_mov_b32_e32 v233, 0
	v_mov_b32_e32 v234, 0
	v_mov_b32_e32 v235, 0
	v_mov_b32_e32 v236, 0
	v_mov_b32_e32 v237, 0
	v_mov_b32_e32 v238, 0
	v_mov_b32_e32 v239, 0
	v_mov_b32_e32 v240, 0
	v_mov_b32_e32 v241, 0
	v_mov_b32_e32 v242, 0
	v_mov_b32_e32 v243, 0
	v_mov_b32_e32 v244, 0
	v_mov_b32_e32 v245, 0
	v_mov_b32_e32 v246, 0
	v_mov_b32_e32 v247, 0
	v_mov_b32_e32 v248, 0
	v_mov_b32_e32 v249, 0
	v_mov_b32_e32 v252, 0
	v_mov_b32_e32 v253, 0
	v_mov_b32_e32 v254, 0
	v_mov_b32_e32 v255, 0
	ds_read_b128 v[164:167], v209
	ds_read_b128 v[168:171], v210
	ds_read_b128 v[172:175], v211
	ds_read_b128 v[176:179], v212
	s_waitcnt lgkmcnt(3)
	v_mfma_f32_32x32x16_bf16 v[98:113], v[164:167], v[126:129], v[66:81]
	s_waitcnt lgkmcnt(2)
	v_mfma_f32_32x32x16_bf16 v[98:113], v[168:171], v[122:125], v[98:113]
	s_waitcnt lgkmcnt(1)
	v_mfma_f32_32x32x16_bf16 v[98:113], v[172:175], v[118:121], v[98:113]
	s_waitcnt lgkmcnt(0)
	v_mfma_f32_32x32x16_bf16 v[98:113], v[176:179], v[114:117], v[98:113]
	s_nop 3
.Lq_even_top:
	s_cmp_eq_u32 s94, s92
	s_cbranch_scc1 .Lq_last
	s_lshr_b32 s0, s94, 1
	s_and_b32 s0, s0, 3
	s_lshl_b32 s95, s0, 15
	v_add_u32_e32 v203, s95, v209
	ds_read_b128 v[164:167], v203 offset:4096
	v_add_u32_e32 v204, s95, v210
	ds_read_b128 v[168:171], v204 offset:4096
	v_add_u32_e32 v203, s95, v211
	ds_read_b128 v[172:175], v203 offset:4096
	v_add_u32_e32 v204, s95, v212
	ds_read_b128 v[176:179], v204 offset:4096
	v_add_u32_e32 v208, s95, v133
	v_add_u32_e32 v213, s95, v205
	s_waitcnt lgkmcnt(4)
	v_mfma_f32_32x32x16_bf16 v[50:65], v[220:223], v[82:85], v[50:65]
	ds_read_b128 v[220:223], v208 offset:16384
	v_max3_f32 v1, v98, v99, v100
	v_max3_f32 v1, v1, v101, v102
	v_max3_f32 v1, v1, v103, v104
	v_max3_f32 v1, v1, v105, v106
	v_max3_f32 v1, v1, v107, v108
	v_mfma_f32_32x32x16_bf16 v[34:49], v[226:229], v[82:85], v[34:49]
	ds_read_b128 v[226:229], v208 offset:20480
	v_max3_f32 v1, v1, v109, v110
	v_max3_f32 v1, v1, v111, v112
	v_max_f32_e32 v224, v1, v113
	v_max_f32_e32 v225, v1, v113
	v_mfma_f32_32x32x16_bf16 v[18:33], v[230:233], v[82:85], v[18:33]
	ds_read_b128 v[230:233], v208 offset:24576
	s_nop 1
	v_permlane32_swap_b32_e32 v224, v225
	v_max_f32_e32 v1, v224, v225
	v_cmp_lt_f32_e32 vcc, s96, v1
	s_cbranch_vccnz .Lq_re_e
.Lq_rec_e:
	v_mfma_f32_32x32x16_bf16 v[2:17], v[234:237], v[82:85], v[2:17]
	ds_read_b128 v[234:237], v208 offset:28672
	v_exp_f32_e32 v98, v98
	v_exp_f32_e32 v99, v99
	v_exp_f32_e32 v100, v100
	v_add_f32_e32 v251, v98, v99
	v_exp_f32_e32 v101, v101
	v_mfma_f32_32x32x16_bf16 v[50:65], v[238:241], v[86:89], v[50:65]
	ds_read_b128 v[238:241], v213 offset:16384
	v_exp_f32_e32 v102, v102
	v_add_f32_e32 v251, v251, v100
	v_exp_f32_e32 v103, v103
	v_add_f32_e32 v251, v251, v101
	v_exp_f32_e32 v104, v104
	v_mfma_f32_32x32x16_bf16 v[34:49], v[242:245], v[86:89], v[34:49]
	ds_read_b128 v[242:245], v213 offset:20480
	v_add_f32_e32 v251, v251, v102
	v_exp_f32_e32 v105, v105
	v_add_f32_e32 v251, v251, v103
	v_cvt_pk_bf16_f32 v98, v98, v99
	v_add_f32_e32 v251, v251, v104
	v_mfma_f32_32x32x16_bf16 v[18:33], v[246:249], v[86:89], v[18:33]
	ds_read_b128 v[246:249], v213 offset:24576
	v_cvt_pk_bf16_f32 v99, v100, v101
	v_cvt_pk_bf16_f32 v100, v102, v103
	v_cvt_pk_bf16_f32 v101, v104, v105
	v_add_f32_e32 v251, v251, v105
	v_mfma_f32_32x32x16_bf16 v[2:17], v[252:255], v[86:89], v[2:17]
	ds_read_b128 v[252:255], v213 offset:28672
	v_exp_f32_e32 v106, v106
	v_exp_f32_e32 v107, v107
	v_exp_f32_e32 v108, v108
	v_add_f32_e32 v251, v251, v106
	s_cmp_lg_u32 s59, 0
	s_cbranch_scc1 .Lq_rl_e
.Lq_rlc_e:
	s_waitcnt lgkmcnt(8)
	v_mfma_f32_32x32x16_bf16 v[82:97], v[164:167], v[126:129], v[66:81]
	v_exp_f32_e32 v109, v109
	v_add_f32_e32 v251, v251, v107
	v_exp_f32_e32 v110, v110
	v_add_f32_e32 v251, v251, v108
	v_mfma_f32_32x32x16_bf16 v[82:97], v[168:171], v[122:125], v[82:97]
	v_exp_f32_e32 v111, v111
	v_add_f32_e32 v251, v251, v109
	v_exp_f32_e32 v112, v112
	v_add_f32_e32 v251, v251, v110
	v_mfma_f32_32x32x16_bf16 v[82:97], v[172:175], v[118:121], v[82:97]
	v_exp_f32_e32 v113, v113
	v_add_f32_e32 v251, v251, v111
	v_cvt_pk_bf16_f32 v102, v106, v107
	v_add_f32_e32 v251, v251, v112
	v_mfma_f32_32x32x16_bf16 v[82:97], v[176:179], v[114:117], v[82:97]
	v_cvt_pk_bf16_f32 v103, v108, v109
	v_cvt_pk_bf16_f32 v104, v110, v111
	v_cvt_pk_bf16_f32 v105, v112, v113
	v_add_f32_e32 v251, v251, v113
	v_add_f32_e32 v218, v218, v251
	s_add_i32 s94, s94, 1
	s_lshr_b32 s0, s94, 1
	s_and_b32 s0, s0, 3
	s_lshl_b32 s95, s0, 15
	s_add_i32 s0, s94, 1
	s_lshr_b32 s58, s0, 1
	s_add_i32 s1, s93, 1
	s_cmp_le_u32 s58, s1
	s_cbranch_scc1 .Lq_w4_o
	s_waitcnt vmcnt(0)
	s_branch .Lq_wd_o
; #define LAS __attribute__((address_space(3)))
; __device__ __forceinline__ void diff_unit_lds(LAS unsigned char* lds, const bf16* Qd, const bf16* Kd, const bf16* VdT, bf16* MIX, const float* ghead, float lam, int head, int u, int wave, int lane) {
;     ...
;         if (T <= Tlast) {
;             const bool part = (T == Tlast);
;             const bool masked = part && (h == 1);
;             f32x16 S0 = NEGM, S1 = NEGM;
; #pragma unroll
;             for (int ds = 0; ds < 4; ++ds) S0 = MFMA32(*(const LAS bf16x8*)(st + koff + (((2 * ds + h) ^ kx) << 4)), qf[ds], S0);
;             if (!part) {
; #pragma unroll
;                 for (int ds = 0; ds < 4; ++ds) S1 = MFMA32(*(const LAS bf16x8*)(st + koff + 4096 + (((2 * ds + h) ^ kx) << 4)), qf[ds], S1);
;             }
;             float tmax = S0[0];
; #pragma unroll
;             for (int i = 1; i < 16; ++i) tmax = fmaxf(tmax, S0[i]);
;             if (masked) tmax = -1e30f;
;             if (!part) {
; #pragma unroll
;                 for (int i = 0; i < 16; ++i) tmax = fmaxf(tmax, S1[i]);
;             }
;             tmax = fmaxf(tmax, xhalf(tmax, h));
;             if (T == 0 || __any(tmax > 8.0f)) {
;                 const float delta = (T == 0) ? tmax : fmaxf(tmax, 0.f), alpha = (T == 0) ? 1.0f : __builtin_amdgcn_exp2f(-delta);
;                 l *= alpha;
; #pragma unroll
;                 for (int b = 0; b < 4; ++b)
; #pragma unroll
;                     for (int i = 0; i < 16; ++i) O[b][i] *= alpha;
;                 m_used += delta;
; #pragma unroll
;                 for (int i = 0; i < 16; ++i) { NEGM[i] = -m_used; S0[i] -= delta; S1[i] -= delta; }
;             }
;             {
;                 float p[16]; float ps = 0.f;
; #pragma unroll
;                 for (int i = 0; i < 16; ++i) { p[i] = __builtin_amdgcn_exp2f(S0[i]); ps += p[i]; }
;                 if (masked) {
; #pragma unroll
;                     for (int i = 0; i < 16; ++i) p[i] = 0.f;
;                     ps = 0.f;
;                 }
;                 l += ps;
;                 const bf16x8 pk0 = pack8(p[0], p[1], p[2], p[3], p[4], p[5], p[6], p[7]);
;                 const bf16x8 pk1 = pack8(p[8], p[9], p[10], p[11], p[12], p[13], p[14], p[15]);
; #pragma unroll
;                 for (int b = 0; b < 4; ++b) {
;                     const bf16x8 v0 = *(const LAS bf16x8*)(st + voff + b * 4096 + (((2 * h) ^ vx) << 4));
.Lq_w4_o:
	s_waitcnt vmcnt(4)
.Lq_wd_o:
	s_barrier
	s_cmp_lt_u32 s58, 2
	s_cbranch_scc1 .Lq_nodma_o
	s_cmp_gt_u32 s58, s93
	s_cbranch_scc1 .Lq_nodma_o
	s_add_i32 s6, s58, 2
	s_and_b32 s0, s6, 3
	s_lshl_b32 s0, s0, 15
	s_add_i32 s1, s0, s33
	s_mov_b32 s7, m0
	s_lshl_b32 s8, s6, 16
	s_mov_b32 s9, 0
	v_lshl_add_u64 v[180:181], v[158:159], 0, s[8:9]
	s_mov_b32 s0, s1
	s_mov_b32 m0, s0
	s_nop 0
	global_load_lds_dwordx4 v[180:181], off
	s_add_i32 s8, s8, 0x80
	v_lshl_add_u64 v[182:183], v[158:159], 0, s[8:9]
	s_add_i32 s0, s1, 0x2000
	s_mov_b32 m0, s0
	s_nop 0
	global_load_lds_dwordx4 v[182:183], off
	s_lshl_b32 s8, s6, 7
	v_lshl_add_u64 v[184:185], v[156:157], 0, s[8:9]
	s_add_i32 s0, s1, 0x4000
	s_mov_b32 m0, s0
	s_nop 0
	global_load_lds_dwordx4 v[184:185], off
	v_lshl_add_u64 v[186:187], v[162:163], 0, s[8:9]
	s_add_i32 s0, s1, 0x6000
	s_mov_b32 m0, s0
	s_nop 0
	global_load_lds_dwordx4 v[186:187], off
	s_mov_b32 m0, s7
.Lq_nodma_o:
	s_and_b32 s0, s58, 3
	s_lshl_b32 s58, s0, 15
	v_add_u32_e32 v203, s58, v209
	ds_read_b128 v[164:167], v203
	v_add_u32_e32 v204, s58, v210
	ds_read_b128 v[168:171], v204
	v_add_u32_e32 v203, s58, v211
	ds_read_b128 v[172:175], v203
	v_add_u32_e32 v204, s58, v212
	ds_read_b128 v[176:179], v204
	v_add_u32_e32 v208, s95, v206
	v_add_u32_e32 v213, s95, v207
	s_waitcnt lgkmcnt(4)
	v_mfma_f32_32x32x16_bf16 v[50:65], v[220:223], v[98:101], v[50:65]
	ds_read_b128 v[220:223], v208 offset:16384
	v_max3_f32 v1, v82, v83, v84
	v_max3_f32 v1, v1, v85, v86
	v_max3_f32 v1, v1, v87, v88
	v_max3_f32 v1, v1, v89, v90
	v_max3_f32 v1, v1, v91, v92
	v_mfma_f32_32x32x16_bf16 v[34:49], v[226:229], v[98:101], v[34:49]
	ds_read_b128 v[226:229], v208 offset:20480
	v_max3_f32 v1, v1, v93, v94
	v_max3_f32 v1, v1, v95, v96
	v_max_f32_e32 v224, v1, v97
	v_max_f32_e32 v225, v1, v97
	v_mfma_f32_32x32x16_bf16 v[18:33], v[230:233], v[98:101], v[18:33]
	ds_read_b128 v[230:233], v208 offset:24576
	s_nop 1
	v_permlane32_swap_b32_e32 v224, v225
	v_max_f32_e32 v1, v224, v225
	v_cmp_lt_f32_e32 vcc, s96, v1
	s_cbranch_vccnz .Lq_re_o
.Lq_rec_o:
	v_mfma_f32_32x32x16_bf16 v[2:17], v[234:237], v[98:101], v[2:17]
	ds_read_b128 v[234:237], v208 offset:28672
	v_exp_f32_e32 v82, v82
	v_exp_f32_e32 v83, v83
	v_exp_f32_e32 v84, v84
	v_add_f32_e32 v251, v82, v83
	v_exp_f32_e32 v85, v85
	v_mfma_f32_32x32x16_bf16 v[50:65], v[238:241], v[102:105], v[50:65]
	ds_read_b128 v[238:241], v213 offset:16384
	v_exp_f32_e32 v86, v86
	v_add_f32_e32 v251, v251, v84
	v_exp_f32_e32 v87, v87
	v_add_f32_e32 v251, v251, v85
	v_exp_f32_e32 v88, v88
	v_mfma_f32_32x32x16_bf16 v[34:49], v[242:245], v[102:105], v[34:49]
	ds_read_b128 v[242:245], v213 offset:20480
	v_add_f32_e32 v251, v251, v86
	v_exp_f32_e32 v89, v89
	v_add_f32_e32 v251, v251, v87
	v_cvt_pk_bf16_f32 v82, v82, v83
	v_add_f32_e32 v251, v251, v88
	v_mfma_f32_32x32x16_bf16 v[18:33], v[246:249], v[102:105], v[18:33]
	ds_read_b128 v[246:249], v213 offset:24576
	v_cvt_pk_bf16_f32 v83, v84, v85
	v_cvt_pk_bf16_f32 v84, v86, v87
	v_cvt_pk_bf16_f32 v85, v88, v89
	v_add_f32_e32 v251, v251, v89
	v_mfma_f32_32x32x16_bf16 v[2:17], v[252:255], v[102:105], v[2:17]
	ds_read_b128 v[252:255], v213 offset:28672
	v_exp_f32_e32 v90, v90
	v_exp_f32_e32 v91, v91
	v_exp_f32_e32 v92, v92
	v_add_f32_e32 v251, v251, v90
	s_cmp_lg_u32 s59, 0
	s_cbranch_scc1 .Lq_rl_o
.Lq_rlc_o:
	s_waitcnt lgkmcnt(8)
	v_mfma_f32_32x32x16_bf16 v[98:113], v[164:167], v[126:129], v[66:81]
	v_exp_f32_e32 v93, v93
	v_add_f32_e32 v251, v251, v91
	v_exp_f32_e32 v94, v94
	v_add_f32_e32 v251, v251, v92
	v_mfma_f32_32x32x16_bf16 v[98:113], v[168:171], v[122:125], v[98:113]
	v_exp_f32_e32 v95, v95
	v_add_f32_e32 v251, v251, v93
	v_exp_f32_e32 v96, v96
	v_add_f32_e32 v251, v251, v94
	v_mfma_f32_32x32x16_bf16 v[98:113], v[172:175], v[118:121], v[98:113]
	v_exp_f32_e32 v97, v97
	v_add_f32_e32 v251, v251, v95
	v_cvt_pk_bf16_f32 v86, v90, v91
	v_add_f32_e32 v251, v251, v96
	v_mfma_f32_32x32x16_bf16 v[98:113], v[176:179], v[114:117], v[98:113]
	v_cvt_pk_bf16_f32 v87, v92, v93
	v_cvt_pk_bf16_f32 v88, v94, v95
	v_cvt_pk_bf16_f32 v89, v96, v97
	v_add_f32_e32 v251, v251, v97
	v_add_f32_e32 v218, v218, v251
	s_add_i32 s94, s94, 1
	s_branch .Lq_even_top
.Lq_last:
	s_lshr_b32 s0, s94, 1
	s_and_b32 s0, s0, 3
	s_lshl_b32 s95, s0, 15
	v_add_u32_e32 v208, s95, v133
	v_add_u32_e32 v213, s95, v205
	s_waitcnt lgkmcnt(0)
	v_mfma_f32_32x32x16_bf16 v[50:65], v[220:223], v[82:85], v[50:65]
	ds_read_b128 v[220:223], v208 offset:16384
	v_max3_f32 v1, v98, v99, v100
	v_max3_f32 v1, v1, v101, v102
	v_max3_f32 v1, v1, v103, v104
	v_max3_f32 v1, v1, v105, v106
	v_max3_f32 v1, v1, v107, v108
	v_mfma_f32_32x32x16_bf16 v[34:49], v[226:229], v[82:85], v[34:49]
	ds_read_b128 v[226:229], v208 offset:20480
	v_max3_f32 v1, v1, v109, v110
	v_max3_f32 v1, v1, v111, v112
	v_max_f32_e32 v1, v1, v113
	v_cndmask_b32_e64 v1, v1, v217, s[2:3]
	v_mov_b32_e32 v224, v1
	v_mov_b32_e32 v225, v1
	v_mfma_f32_32x32x16_bf16 v[18:33], v[230:233], v[82:85], v[18:33]
	ds_read_b128 v[230:233], v208 offset:24576
	s_nop 1
	v_permlane32_swap_b32_e32 v224, v225
	v_max_f32_e32 v1, v224, v225
	v_cmp_lt_f32_e32 vcc, s96, v1
	s_cbranch_vccnz .Lq_re_m
; #define LAS __attribute__((address_space(3)))
; #define MFMA32(a, b, c) __builtin_amdgcn_mfma_f32_32x32x16_bf16((a), (b), (c), 0, 0, 0)
; __device__ __forceinline__ void diff_unit_lds(LAS unsigned char* lds, const bf16* Qd, const bf16* Kd, const bf16* VdT, bf16* MIX, const float* ghead, float lam, int head, int u, int wave, int lane) {
;     ...
;             if (masked) tmax = -1e30f;
;             if (!part) {
; #pragma unroll
;                 for (int i = 0; i < 16; ++i) tmax = fmaxf(tmax, S1[i]);
;             }
;             tmax = fmaxf(tmax, xhalf(tmax, h));
;             if (T == 0 || __any(tmax > 8.0f)) {
;                 const float delta = (T == 0) ? tmax : fmaxf(tmax, 0.f), alpha = (T == 0) ? 1.0f : __builtin_amdgcn_exp2f(-delta);
;                 l *= alpha;
; #pragma unroll
;                 for (int b = 0; b < 4; ++b)
; #pragma unroll
;                     for (int i = 0; i < 16; ++i) O[b][i] *= alpha;
;                 m_used += delta;
; #pragma unroll
;                 for (int i = 0; i < 16; ++i) { NEGM[i] = -m_used; S0[i] -= delta; S1[i] -= delta; }
;             }
;             {
;                 float p[16]; float ps = 0.f;
; #pragma unroll
;                 for (int i = 0; i < 16; ++i) { p[i] = __builtin_amdgcn_exp2f(S0[i]); ps += p[i]; }
;                 if (masked) {
; #pragma unroll
;                     for (int i = 0; i < 16; ++i) p[i] = 0.f;
;                     ps = 0.f;
;                 }
;                 l += ps;
;                 const bf16x8 pk0 = pack8(p[0], p[1], p[2], p[3], p[4], p[5], p[6], p[7]);
;                 const bf16x8 pk1 = pack8(p[8], p[9], p[10], p[11], p[12], p[13], p[14], p[15]);
; #pragma unroll
;                 for (int b = 0; b < 4; ++b) {
;                     const bf16x8 v0 = *(const LAS bf16x8*)(st + voff + b * 4096 + (((2 * h) ^ vx) << 4));
;                     const bf16x8 v1 = *(const LAS bf16x8*)(st + voff + b * 4096 + (((2 * h + 1) ^ vx) << 4));
;                     O[b] = MFMA32(v0, pk0, O[b]); O[b] = MFMA32(v1, pk1, O[b]);
;                 }
;             }
.Lq_rec_m:
	v_mfma_f32_32x32x16_bf16 v[2:17], v[234:237], v[82:85], v[2:17]
	ds_read_b128 v[234:237], v208 offset:28672
	v_exp_f32_e32 v98, v98
	v_exp_f32_e32 v99, v99
	v_exp_f32_e32 v100, v100
	v_add_f32_e32 v251, v98, v99
	v_exp_f32_e32 v101, v101
	v_exp_f32_e32 v102, v102
	v_add_f32_e32 v251, v251, v100
	v_exp_f32_e32 v103, v103
	v_add_f32_e32 v251, v251, v101
	v_exp_f32_e32 v104, v104
	v_mfma_f32_32x32x16_bf16 v[50:65], v[238:241], v[86:89], v[50:65]
	ds_read_b128 v[238:241], v213 offset:16384
	v_add_f32_e32 v251, v251, v102
	v_exp_f32_e32 v105, v105
	v_add_f32_e32 v251, v251, v103
	v_cvt_pk_bf16_f32 v98, v98, v99
	v_add_f32_e32 v251, v251, v104
	v_cvt_pk_bf16_f32 v99, v100, v101
	v_cvt_pk_bf16_f32 v100, v102, v103
	v_cvt_pk_bf16_f32 v101, v104, v105
	v_add_f32_e32 v251, v251, v105
	v_exp_f32_e32 v106, v106
	v_mfma_f32_32x32x16_bf16 v[34:49], v[242:245], v[86:89], v[34:49]
	ds_read_b128 v[242:245], v213 offset:20480
	v_exp_f32_e32 v107, v107
	v_exp_f32_e32 v108, v108
	v_add_f32_e32 v251, v251, v106
	v_exp_f32_e32 v109, v109
	v_add_f32_e32 v251, v251, v107
	v_exp_f32_e32 v110, v110
	v_add_f32_e32 v251, v251, v108
	v_exp_f32_e32 v111, v111
	v_add_f32_e32 v251, v251, v109
	v_exp_f32_e32 v112, v112
	v_mfma_f32_32x32x16_bf16 v[18:33], v[246:249], v[86:89], v[18:33]
	ds_read_b128 v[246:249], v213 offset:24576
	v_add_f32_e32 v251, v251, v110
	v_exp_f32_e32 v113, v113
	v_add_f32_e32 v251, v251, v111
	v_cvt_pk_bf16_f32 v102, v106, v107
	v_add_f32_e32 v251, v251, v112
	v_cvt_pk_bf16_f32 v103, v108, v109
	v_cvt_pk_bf16_f32 v104, v110, v111
	v_cvt_pk_bf16_f32 v105, v112, v113
	v_add_f32_e32 v251, v251, v113
	v_mfma_f32_32x32x16_bf16 v[2:17], v[252:255], v[86:89], v[2:17]
	ds_read_b128 v[252:255], v213 offset:28672
	v_cndmask_b32_e64 v98, v98, 0, s[2:3]
	v_cndmask_b32_e64 v99, v99, 0, s[2:3]
	v_cndmask_b32_e64 v100, v100, 0, s[2:3]
	v_cndmask_b32_e64 v101, v101, 0, s[2:3]
	v_cndmask_b32_e64 v102, v102, 0, s[2:3]
	v_cndmask_b32_e64 v103, v103, 0, s[2:3]
	v_cndmask_b32_e64 v104, v104, 0, s[2:3]
	v_cndmask_b32_e64 v105, v105, 0, s[2:3]
	v_cndmask_b32_e64 v251, v251, 0, s[2:3]
	s_cmp_lg_u32 s59, 0
	s_cbranch_scc1 .Lq_rl_m
.Lq_rlc_m:
	v_add_f32_e32 v218, v218, v251
	s_waitcnt lgkmcnt(0)
	v_mfma_f32_32x32x16_bf16 v[50:65], v[220:223], v[98:101], v[50:65]
	v_mfma_f32_32x32x16_bf16 v[34:49], v[226:229], v[98:101], v[34:49]
	v_mfma_f32_32x32x16_bf16 v[18:33], v[230:233], v[98:101], v[18:33]
	v_mfma_f32_32x32x16_bf16 v[2:17], v[234:237], v[98:101], v[2:17]
	v_mfma_f32_32x32x16_bf16 v[50:65], v[238:241], v[102:105], v[50:65]
	v_mfma_f32_32x32x16_bf16 v[34:49], v[242:245], v[102:105], v[34:49]
	v_mfma_f32_32x32x16_bf16 v[18:33], v[246:249], v[102:105], v[18:33]
	v_mfma_f32_32x32x16_bf16 v[2:17], v[252:255], v[102:105], v[2:17]
	s_cmp_lg_u32 s23, 0
	s_cbranch_scc1 .Lq_done
	s_waitcnt vmcnt(0)
	s_barrier
.Lq_done:
	s_nop 7
	s_branch .LBB0_496
.Lq_re_e:
	v_max_f32_e32 v224, s97, v1
	v_exp_f32_e64 v225, -v224
	v_add_f32_e32 v219, v219, v224
	v_xor_b32_e32 v66, 0x80000000, v219
	v_mov_b32_e32 v67, v66
	v_mov_b32_e32 v68, v66
	v_mov_b32_e32 v69, v66
	v_mov_b32_e32 v70, v66
	v_mov_b32_e32 v71, v66
	v_mov_b32_e32 v72, v66
	v_mov_b32_e32 v73, v66
	v_mov_b32_e32 v74, v66
	v_mov_b32_e32 v75, v66
	v_mov_b32_e32 v76, v66
	v_mov_b32_e32 v77, v66
	v_mov_b32_e32 v78, v66
	v_mov_b32_e32 v79, v66
	v_mov_b32_e32 v80, v66
	v_mov_b32_e32 v81, v66
	v_sub_f32_e32 v98, v98, v224
	v_sub_f32_e32 v99, v99, v224
	v_sub_f32_e32 v100, v100, v224
	v_sub_f32_e32 v101, v101, v224
	v_sub_f32_e32 v102, v102, v224
	v_sub_f32_e32 v103, v103, v224
	v_sub_f32_e32 v104, v104, v224
	v_sub_f32_e32 v105, v105, v224
	v_sub_f32_e32 v106, v106, v224
	v_sub_f32_e32 v107, v107, v224
	v_sub_f32_e32 v108, v108, v224
	v_sub_f32_e32 v109, v109, v224
	v_sub_f32_e32 v110, v110, v224
	v_sub_f32_e32 v111, v111, v224
	v_sub_f32_e32 v112, v112, v224
	v_sub_f32_e32 v113, v113, v224
	s_mov_b32 s59, 1
	s_mov_b32 s96, 0x41000000
	s_mov_b32 s97, 0
	s_branch .Lq_rec_e
.Lq_rl_e:
	s_nop 11
	s_nop 1
	v_mul_f32_e32 v218, v218, v225
	v_mul_f32_e32 v2, v2, v225
	v_mul_f32_e32 v3, v3, v225
	v_mul_f32_e32 v4, v4, v225
	v_mul_f32_e32 v5, v5, v225
	v_mul_f32_e32 v6, v6, v225
	v_mul_f32_e32 v7, v7, v225
	v_mul_f32_e32 v8, v8, v225
	v_mul_f32_e32 v9, v9, v225
	v_mul_f32_e32 v10, v10, v225
	v_mul_f32_e32 v11, v11, v225
	v_mul_f32_e32 v12, v12, v225
	v_mul_f32_e32 v13, v13, v225
	v_mul_f32_e32 v14, v14, v225
	v_mul_f32_e32 v15, v15, v225
	v_mul_f32_e32 v16, v16, v225
	v_mul_f32_e32 v17, v17, v225
	v_mul_f32_e32 v18, v18, v225
	v_mul_f32_e32 v19, v19, v225
	v_mul_f32_e32 v20, v20, v225
	v_mul_f32_e32 v21, v21, v225
	v_mul_f32_e32 v22, v22, v225
	v_mul_f32_e32 v23, v23, v225
	v_mul_f32_e32 v24, v24, v225
	v_mul_f32_e32 v25, v25, v225
	v_mul_f32_e32 v26, v26, v225
	v_mul_f32_e32 v27, v27, v225
	v_mul_f32_e32 v28, v28, v225
	v_mul_f32_e32 v29, v29, v225
	v_mul_f32_e32 v30, v30, v225
	v_mul_f32_e32 v31, v31, v225
	v_mul_f32_e32 v32, v32, v225
	v_mul_f32_e32 v33, v33, v225
	v_mul_f32_e32 v34, v34, v225
	v_mul_f32_e32 v35, v35, v225
	v_mul_f32_e32 v36, v36, v225
	v_mul_f32_e32 v37, v37, v225
	v_mul_f32_e32 v38, v38, v225
	v_mul_f32_e32 v39, v39, v225
	v_mul_f32_e32 v40, v40, v225
	v_mul_f32_e32 v41, v41, v225
	v_mul_f32_e32 v42, v42, v225
	v_mul_f32_e32 v43, v43, v225
	v_mul_f32_e32 v44, v44, v225
	v_mul_f32_e32 v45, v45, v225
	v_mul_f32_e32 v46, v46, v225
	v_mul_f32_e32 v47, v47, v225
	v_mul_f32_e32 v48, v48, v225
	v_mul_f32_e32 v49, v49, v225
	v_mul_f32_e32 v50, v50, v225
	v_mul_f32_e32 v51, v51, v225
	v_mul_f32_e32 v52, v52, v225
	v_mul_f32_e32 v53, v53, v225
	v_mul_f32_e32 v54, v54, v225
	v_mul_f32_e32 v55, v55, v225
	v_mul_f32_e32 v56, v56, v225
	v_mul_f32_e32 v57, v57, v225
	v_mul_f32_e32 v58, v58, v225
	v_mul_f32_e32 v59, v59, v225
	v_mul_f32_e32 v60, v60, v225
	v_mul_f32_e32 v61, v61, v225
	v_mul_f32_e32 v62, v62, v225
	v_mul_f32_e32 v63, v63, v225
	v_mul_f32_e32 v64, v64, v225
	v_mul_f32_e32 v65, v65, v225
	s_mov_b32 s59, 0
	s_branch .Lq_rlc_e
.Lq_re_o:
	v_max_f32_e32 v224, s97, v1
	v_exp_f32_e64 v225, -v224
	v_add_f32_e32 v219, v219, v224
	v_xor_b32_e32 v66, 0x80000000, v219
	v_mov_b32_e32 v67, v66
	v_mov_b32_e32 v68, v66
	v_mov_b32_e32 v69, v66
	v_mov_b32_e32 v70, v66
	v_mov_b32_e32 v71, v66
	v_mov_b32_e32 v72, v66
	v_mov_b32_e32 v73, v66
	v_mov_b32_e32 v74, v66
	v_mov_b32_e32 v75, v66
	v_mov_b32_e32 v76, v66
	v_mov_b32_e32 v77, v66
	v_mov_b32_e32 v78, v66
	v_mov_b32_e32 v79, v66
	v_mov_b32_e32 v80, v66
	v_mov_b32_e32 v81, v66
	v_sub_f32_e32 v82, v82, v224
	v_sub_f32_e32 v83, v83, v224
	v_sub_f32_e32 v84, v84, v224
	v_sub_f32_e32 v85, v85, v224
	v_sub_f32_e32 v86, v86, v224
	v_sub_f32_e32 v87, v87, v224
	v_sub_f32_e32 v88, v88, v224
	v_sub_f32_e32 v89, v89, v224
	v_sub_f32_e32 v90, v90, v224
	v_sub_f32_e32 v91, v91, v224
	v_sub_f32_e32 v92, v92, v224
	v_sub_f32_e32 v93, v93, v224
	v_sub_f32_e32 v94, v94, v224
	v_sub_f32_e32 v95, v95, v224
	v_sub_f32_e32 v96, v96, v224
	v_sub_f32_e32 v97, v97, v224
	s_mov_b32 s59, 1
	s_mov_b32 s96, 0x41000000
	s_mov_b32 s97, 0
	s_branch .Lq_rec_o
